# v45 with the conversion unit's last tile peeled: no redundant clamped prefetch of a 19th tile per wave
# baseline (speedup 1.0000x reference)
.LBB0_357:
	s_andn2_b64 vcc, exec, s[14:15]
	s_cbranch_vccnz .LBB0_280
	s_cmp_eq_u32 s2, 6
	s_cselect_b32 s4, 1, 0
	s_lshl_b32 s2, s50, 1
	s_add_i32 s2, s2, s4
	s_add_i32 s2, s2, s89
	s_mul_i32 s2, s2, 0x90
	s_add_i32 s2, s2, s76
	s_add_i32 s86, s2, 0x88
	s_load_dwordx2 s[78:79], s[0:1], 0x70
	s_load_dwordx2 s[80:81], s[0:1], 0x80
	s_load_dwordx2 s[82:83], s[0:1], 0x88
	s_load_dwordx2 s[16:17], s[0:1], 0xa0
	v_and_b32_e32 v3, 63, v0
	v_lshrrev_b32_e32 v84, 4, v3
	v_and_b32_e32 v85, 15, v3
	v_lshlrev_b32_e32 v85, 4, v85
	s_mul_i32 s4, s76, 0x2400
	v_mul_u32_u24_e32 v86, 36, v85
	v_lshl_add_u32 v86, v84, 4, v86
	v_add_u32_e32 v86, s4, v86
	v_lshrrev_b32_e32 v87, 3, v3
	v_mul_u32_u24_e32 v87, 0x90, v87
	v_and_b32_e32 v88, 7, v3
	v_lshl_add_u32 v87, v88, 4, v87
	v_add_u32_e32 v87, s4, v87
	v_lshlrev_b32_e32 v88, 4, v3
	s_movk_i32 s41, 8
	s_waitcnt lgkmcnt(0)
	s_mov_b32 s12, s2
	s_mov_b64 s[10:11], s[80:81]
	s_movk_i32 s4, 0x1000
	s_mov_b32 s5, 8
	s_mov_b32 s6, 0x8400000
	s_cmpk_lt_u32 s12, 0x1000
	s_cselect_b64 s[10:11], s[78:79], s[10:11]
	s_cselect_b32 s4, 0, s4
	s_cselect_b32 s5, 6, s5
	s_cselect_b32 s6, 0x6400000, s6
	s_cmpk_lt_u32 s12, 0x5000
	s_cselect_b64 s[10:11], s[10:11], s[82:83]
	s_cselect_b32 s4, s4, 0x5000
	s_cselect_b32 s5, s5, 6
	s_cselect_b32 s6, s6, 0x10400000
	s_cselect_b32 s7, 6, 8
	s_sub_i32 s12, s12, s4
	s_lshr_b32 s4, s12, s5
	s_bfm_b32 s8, s5, 0
	s_and_b32 s12, s12, s8
	s_lshr_b32 s8, s12, 2
	s_lshl_b32 s8, s8, s7
	s_add_i32 s8, s8, s4
	s_lshl_b32 s8, s8, 15
	s_and_b32 s9, s12, 3
	s_lshl_b32 s9, s9, 13
	s_add_i32 s8, s8, s9
	s_add_u32 s8, s8, s6
	s_add_u32 s48, s8, s16
	s_addc_u32 s49, s17, 0
	s_add_i32 s7, s5, 14
	s_lshl_b32 s4, s4, s7
	s_lshl_b32 s12, s12, 8
	s_add_i32 s4, s4, s12
	s_add_u32 s10, s10, s4
	s_addc_u32 s11, s11, 0
	s_add_i32 s7, s5, 8
	s_lshl_b32 s43, 1, s7
	s_mul_i32 s45, s43, 25
	s_lshl_b32 s47, s43, 3
	v_mad_u32_u24 v89, v84, s47, v85
	global_load_dwordx4 v[20:23], v89, s[10:11] nt
	s_add_u32 s10, s10, s43
	s_addc_u32 s11, s11, 0
	global_load_dwordx4 v[24:27], v89, s[10:11] nt
	s_add_u32 s10, s10, s43
	s_addc_u32 s11, s11, 0
	global_load_dwordx4 v[28:31], v89, s[10:11] nt
	s_add_u32 s10, s10, s43
	s_addc_u32 s11, s11, 0
	global_load_dwordx4 v[32:35], v89, s[10:11] nt
	s_add_u32 s10, s10, s43
	s_addc_u32 s11, s11, 0
	global_load_dwordx4 v[36:39], v89, s[10:11] nt
	s_add_u32 s10, s10, s43
	s_addc_u32 s11, s11, 0
	global_load_dwordx4 v[40:43], v89, s[10:11] nt
	s_add_u32 s10, s10, s43
	s_addc_u32 s11, s11, 0
	global_load_dwordx4 v[44:47], v89, s[10:11] nt
	s_add_u32 s10, s10, s43
	s_addc_u32 s11, s11, 0
	global_load_dwordx4 v[48:51], v89, s[10:11] nt
	s_add_u32 s10, s10, s45
	s_addc_u32 s11, s11, 0
	global_load_dwordx4 v[52:55], v89, s[10:11] nt
	s_add_u32 s10, s10, s43
	s_addc_u32 s11, s11, 0
	global_load_dwordx4 v[56:59], v89, s[10:11] nt
	s_add_u32 s10, s10, s43
	s_addc_u32 s11, s11, 0
	global_load_dwordx4 v[60:63], v89, s[10:11] nt
	s_add_u32 s10, s10, s43
	s_addc_u32 s11, s11, 0
	global_load_dwordx4 v[64:67], v89, s[10:11] nt
	s_add_u32 s10, s10, s43
	s_addc_u32 s11, s11, 0
	global_load_dwordx4 v[68:71], v89, s[10:11] nt
	s_add_u32 s10, s10, s43
	s_addc_u32 s11, s11, 0
	global_load_dwordx4 v[72:75], v89, s[10:11] nt
	s_add_u32 s10, s10, s43
	s_addc_u32 s11, s11, 0
	global_load_dwordx4 v[76:79], v89, s[10:11] nt
	s_add_u32 s10, s10, s43
	s_addc_u32 s11, s11, 0
	global_load_dwordx4 v[80:83], v89, s[10:11] nt
.Lcvh_loop:
	s_mov_b64 s[50:51], s[48:49]
	s_add_i32 s2, s2, 8
	s_min_u32 s12, s2, s86
	s_mov_b64 s[10:11], s[80:81]
	s_movk_i32 s4, 0x1000
	s_mov_b32 s5, 8
	s_mov_b32 s6, 0x8400000
	s_cmpk_lt_u32 s12, 0x1000
	s_cselect_b64 s[10:11], s[78:79], s[10:11]
	s_cselect_b32 s4, 0, s4
	s_cselect_b32 s5, 6, s5
	s_cselect_b32 s6, 0x6400000, s6
	s_cmpk_lt_u32 s12, 0x5000
	s_cselect_b64 s[10:11], s[10:11], s[82:83]
	s_cselect_b32 s4, s4, 0x5000
	s_cselect_b32 s5, s5, 6
	s_cselect_b32 s6, s6, 0x10400000
	s_cselect_b32 s7, 6, 8
	s_sub_i32 s12, s12, s4
	s_lshr_b32 s4, s12, s5
	s_bfm_b32 s8, s5, 0
	s_and_b32 s12, s12, s8
	s_lshr_b32 s8, s12, 2
	s_lshl_b32 s8, s8, s7
	s_add_i32 s8, s8, s4
	s_lshl_b32 s8, s8, 15
	s_and_b32 s9, s12, 3
	s_lshl_b32 s9, s9, 13
	s_add_i32 s8, s8, s9
	s_add_u32 s8, s8, s6
	s_add_u32 s48, s8, s16
	s_addc_u32 s49, s17, 0
	s_add_i32 s7, s5, 14
	s_lshl_b32 s4, s4, s7
	s_lshl_b32 s12, s12, 8
	s_add_i32 s4, s4, s12
	s_add_u32 s10, s10, s4
	s_addc_u32 s11, s11, 0
	s_add_i32 s7, s5, 8
	s_lshl_b32 s43, 1, s7
	s_mul_i32 s45, s43, 25
	s_lshl_b32 s47, s43, 3
	v_mad_u32_u24 v89, v84, s47, v85
	global_load_dwordx4 v[100:103], v89, s[10:11] nt
	s_add_u32 s10, s10, s43
	s_addc_u32 s11, s11, 0
	global_load_dwordx4 v[104:107], v89, s[10:11] nt
	s_add_u32 s10, s10, s43
	s_addc_u32 s11, s11, 0
	global_load_dwordx4 v[108:111], v89, s[10:11] nt
	s_add_u32 s10, s10, s43
	s_addc_u32 s11, s11, 0
	global_load_dwordx4 v[112:115], v89, s[10:11] nt
	s_add_u32 s10, s10, s43
	s_addc_u32 s11, s11, 0
	global_load_dwordx4 v[116:119], v89, s[10:11] nt
	s_add_u32 s10, s10, s43
	s_addc_u32 s11, s11, 0
	global_load_dwordx4 v[120:123], v89, s[10:11] nt
	s_add_u32 s10, s10, s43
	s_addc_u32 s11, s11, 0
	global_load_dwordx4 v[124:127], v89, s[10:11] nt
	s_add_u32 s10, s10, s43
	s_addc_u32 s11, s11, 0
	global_load_dwordx4 v[128:131], v89, s[10:11] nt
	s_add_u32 s10, s10, s45
	s_addc_u32 s11, s11, 0
	global_load_dwordx4 v[132:135], v89, s[10:11] nt
	s_add_u32 s10, s10, s43
	s_addc_u32 s11, s11, 0
	global_load_dwordx4 v[136:139], v89, s[10:11] nt
	s_add_u32 s10, s10, s43
	s_addc_u32 s11, s11, 0
	global_load_dwordx4 v[140:143], v89, s[10:11] nt
	s_add_u32 s10, s10, s43
	s_addc_u32 s11, s11, 0
	global_load_dwordx4 v[144:147], v89, s[10:11] nt
	s_add_u32 s10, s10, s43
	s_addc_u32 s11, s11, 0
	global_load_dwordx4 v[148:151], v89, s[10:11] nt
	s_add_u32 s10, s10, s43
	s_addc_u32 s11, s11, 0
	global_load_dwordx4 v[152:155], v89, s[10:11] nt
	s_add_u32 s10, s10, s43
	s_addc_u32 s11, s11, 0
	global_load_dwordx4 v[156:159], v89, s[10:11] nt
	s_add_u32 s10, s10, s43
	s_addc_u32 s11, s11, 0
	global_load_dwordx4 v[160:163], v89, s[10:11] nt
	s_waitcnt vmcnt(16)
	v_cvt_pk_bf16_f32 v164, v20, v24
	v_cvt_pk_bf16_f32 v165, v28, v32
	v_cvt_pk_bf16_f32 v166, v36, v40
	v_cvt_pk_bf16_f32 v167, v44, v48
	ds_write_b128 v86, v[164:167]
	v_cvt_pk_bf16_f32 v168, v21, v25
	v_cvt_pk_bf16_f32 v169, v29, v33
	v_cvt_pk_bf16_f32 v170, v37, v41
	v_cvt_pk_bf16_f32 v171, v45, v49
	ds_write_b128 v86, v[168:171] offset:144
	v_cvt_pk_bf16_f32 v172, v22, v26
	v_cvt_pk_bf16_f32 v173, v30, v34
	v_cvt_pk_bf16_f32 v174, v38, v42
	v_cvt_pk_bf16_f32 v175, v46, v50
	ds_write_b128 v86, v[172:175] offset:288
	v_cvt_pk_bf16_f32 v176, v23, v27
	v_cvt_pk_bf16_f32 v177, v31, v35
	v_cvt_pk_bf16_f32 v178, v39, v43
	v_cvt_pk_bf16_f32 v179, v47, v51
	ds_write_b128 v86, v[176:179] offset:432
	v_cvt_pk_bf16_f32 v180, v52, v56
	v_cvt_pk_bf16_f32 v181, v60, v64
	v_cvt_pk_bf16_f32 v182, v68, v72
	v_cvt_pk_bf16_f32 v183, v76, v80
	ds_write_b128 v86, v[180:183] offset:64
	v_cvt_pk_bf16_f32 v184, v53, v57
	v_cvt_pk_bf16_f32 v185, v61, v65
	v_cvt_pk_bf16_f32 v186, v69, v73
	v_cvt_pk_bf16_f32 v187, v77, v81
	ds_write_b128 v86, v[184:187] offset:208
	v_cvt_pk_bf16_f32 v188, v54, v58
	v_cvt_pk_bf16_f32 v189, v62, v66
	v_cvt_pk_bf16_f32 v190, v70, v74
	v_cvt_pk_bf16_f32 v191, v78, v82
	ds_write_b128 v86, v[188:191] offset:352
	v_cvt_pk_bf16_f32 v192, v55, v59
	v_cvt_pk_bf16_f32 v193, v63, v67
	v_cvt_pk_bf16_f32 v194, v71, v75
	v_cvt_pk_bf16_f32 v195, v79, v83
	ds_write_b128 v86, v[192:195] offset:496
	s_add_u32 s8, s50, 0x1000
	s_addc_u32 s9, s51, 0
	s_waitcnt lgkmcnt(0)
	ds_read_b128 v[164:167], v87
	ds_read_b128 v[168:171], v87 offset:1152
	ds_read_b128 v[172:175], v87 offset:2304
	ds_read_b128 v[176:179], v87 offset:3456
	ds_read_b128 v[180:183], v87 offset:4608
	ds_read_b128 v[184:187], v87 offset:5760
	ds_read_b128 v[188:191], v87 offset:6912
	ds_read_b128 v[192:195], v87 offset:8064
	s_waitcnt lgkmcnt(7)
	global_store_dwordx4 v88, v[164:167], s[50:51] nt
	s_waitcnt lgkmcnt(6)
	global_store_dwordx4 v88, v[168:171], s[50:51] offset:1024 nt
	s_waitcnt lgkmcnt(5)
	global_store_dwordx4 v88, v[172:175], s[50:51] offset:2048 nt
	s_waitcnt lgkmcnt(4)
	global_store_dwordx4 v88, v[176:179], s[50:51] offset:3072 nt
	s_waitcnt lgkmcnt(3)
	global_store_dwordx4 v88, v[180:183], s[8:9] nt
	s_waitcnt lgkmcnt(2)
	global_store_dwordx4 v88, v[184:187], s[8:9] offset:1024 nt
	s_waitcnt lgkmcnt(1)
	global_store_dwordx4 v88, v[188:191], s[8:9] offset:2048 nt
	s_waitcnt lgkmcnt(0)
	global_store_dwordx4 v88, v[192:195], s[8:9] offset:3072 nt
	s_mov_b64 s[50:51], s[48:49]
	s_add_i32 s2, s2, 8
	s_min_u32 s12, s2, s86
	s_mov_b64 s[10:11], s[80:81]
	s_movk_i32 s4, 0x1000
	s_mov_b32 s5, 8
	s_mov_b32 s6, 0x8400000
	s_cmpk_lt_u32 s12, 0x1000
	s_cselect_b64 s[10:11], s[78:79], s[10:11]
	s_cselect_b32 s4, 0, s4
	s_cselect_b32 s5, 6, s5
	s_cselect_b32 s6, 0x6400000, s6
	s_cmpk_lt_u32 s12, 0x5000
	s_cselect_b64 s[10:11], s[10:11], s[82:83]
	s_cselect_b32 s4, s4, 0x5000
	s_cselect_b32 s5, s5, 6
	s_cselect_b32 s6, s6, 0x10400000
	s_cselect_b32 s7, 6, 8
	s_sub_i32 s12, s12, s4
	s_lshr_b32 s4, s12, s5
	s_bfm_b32 s8, s5, 0
	s_and_b32 s12, s12, s8
	s_lshr_b32 s8, s12, 2
	s_lshl_b32 s8, s8, s7
	s_add_i32 s8, s8, s4
	s_lshl_b32 s8, s8, 15
	s_and_b32 s9, s12, 3
	s_lshl_b32 s9, s9, 13
	s_add_i32 s8, s8, s9
	s_add_u32 s8, s8, s6
	s_add_u32 s48, s8, s16
	s_addc_u32 s49, s17, 0
	s_add_i32 s7, s5, 14
	s_lshl_b32 s4, s4, s7
	s_lshl_b32 s12, s12, 8
	s_add_i32 s4, s4, s12
	s_add_u32 s10, s10, s4
	s_addc_u32 s11, s11, 0
	s_add_i32 s7, s5, 8
	s_lshl_b32 s43, 1, s7
	s_mul_i32 s45, s43, 25
	s_lshl_b32 s47, s43, 3
	v_mad_u32_u24 v89, v84, s47, v85
	global_load_dwordx4 v[20:23], v89, s[10:11] nt
	s_add_u32 s10, s10, s43
	s_addc_u32 s11, s11, 0
	global_load_dwordx4 v[24:27], v89, s[10:11] nt
	s_add_u32 s10, s10, s43
	s_addc_u32 s11, s11, 0
	global_load_dwordx4 v[28:31], v89, s[10:11] nt
	s_add_u32 s10, s10, s43
	s_addc_u32 s11, s11, 0
	global_load_dwordx4 v[32:35], v89, s[10:11] nt
	s_add_u32 s10, s10, s43
	s_addc_u32 s11, s11, 0
	global_load_dwordx4 v[36:39], v89, s[10:11] nt
	s_add_u32 s10, s10, s43
	s_addc_u32 s11, s11, 0
	global_load_dwordx4 v[40:43], v89, s[10:11] nt
	s_add_u32 s10, s10, s43
	s_addc_u32 s11, s11, 0
	global_load_dwordx4 v[44:47], v89, s[10:11] nt
	s_add_u32 s10, s10, s43
	s_addc_u32 s11, s11, 0
	global_load_dwordx4 v[48:51], v89, s[10:11] nt
	s_add_u32 s10, s10, s45
	s_addc_u32 s11, s11, 0
	global_load_dwordx4 v[52:55], v89, s[10:11] nt
	s_add_u32 s10, s10, s43
	s_addc_u32 s11, s11, 0
	global_load_dwordx4 v[56:59], v89, s[10:11] nt
	s_add_u32 s10, s10, s43
	s_addc_u32 s11, s11, 0
	global_load_dwordx4 v[60:63], v89, s[10:11] nt
	s_add_u32 s10, s10, s43
	s_addc_u32 s11, s11, 0
	global_load_dwordx4 v[64:67], v89, s[10:11] nt
	s_add_u32 s10, s10, s43
	s_addc_u32 s11, s11, 0
	global_load_dwordx4 v[68:71], v89, s[10:11] nt
	s_add_u32 s10, s10, s43
	s_addc_u32 s11, s11, 0
	global_load_dwordx4 v[72:75], v89, s[10:11] nt
	s_add_u32 s10, s10, s43
	s_addc_u32 s11, s11, 0
	global_load_dwordx4 v[76:79], v89, s[10:11] nt
	s_add_u32 s10, s10, s43
	s_addc_u32 s11, s11, 0
	global_load_dwordx4 v[80:83], v89, s[10:11] nt
	s_waitcnt vmcnt(16)
	v_cvt_pk_bf16_f32 v164, v100, v104
	v_cvt_pk_bf16_f32 v165, v108, v112
	v_cvt_pk_bf16_f32 v166, v116, v120
	v_cvt_pk_bf16_f32 v167, v124, v128
	ds_write_b128 v86, v[164:167]
	v_cvt_pk_bf16_f32 v168, v101, v105
	v_cvt_pk_bf16_f32 v169, v109, v113
	v_cvt_pk_bf16_f32 v170, v117, v121
	v_cvt_pk_bf16_f32 v171, v125, v129
	ds_write_b128 v86, v[168:171] offset:144
	v_cvt_pk_bf16_f32 v172, v102, v106
	v_cvt_pk_bf16_f32 v173, v110, v114
	v_cvt_pk_bf16_f32 v174, v118, v122
	v_cvt_pk_bf16_f32 v175, v126, v130
	ds_write_b128 v86, v[172:175] offset:288
	v_cvt_pk_bf16_f32 v176, v103, v107
	v_cvt_pk_bf16_f32 v177, v111, v115
	v_cvt_pk_bf16_f32 v178, v119, v123
	v_cvt_pk_bf16_f32 v179, v127, v131
	ds_write_b128 v86, v[176:179] offset:432
	v_cvt_pk_bf16_f32 v180, v132, v136
	v_cvt_pk_bf16_f32 v181, v140, v144
	v_cvt_pk_bf16_f32 v182, v148, v152
	v_cvt_pk_bf16_f32 v183, v156, v160
	ds_write_b128 v86, v[180:183] offset:64
	v_cvt_pk_bf16_f32 v184, v133, v137
	v_cvt_pk_bf16_f32 v185, v141, v145
	v_cvt_pk_bf16_f32 v186, v149, v153
	v_cvt_pk_bf16_f32 v187, v157, v161
	ds_write_b128 v86, v[184:187] offset:208
	v_cvt_pk_bf16_f32 v188, v134, v138
	v_cvt_pk_bf16_f32 v189, v142, v146
	v_cvt_pk_bf16_f32 v190, v150, v154
	v_cvt_pk_bf16_f32 v191, v158, v162
	ds_write_b128 v86, v[188:191] offset:352
	v_cvt_pk_bf16_f32 v192, v135, v139
	v_cvt_pk_bf16_f32 v193, v143, v147
	v_cvt_pk_bf16_f32 v194, v151, v155
	v_cvt_pk_bf16_f32 v195, v159, v163
	ds_write_b128 v86, v[192:195] offset:496
	s_add_u32 s8, s50, 0x1000
	s_addc_u32 s9, s51, 0
	s_waitcnt lgkmcnt(0)
	ds_read_b128 v[164:167], v87
	ds_read_b128 v[168:171], v87 offset:1152
	ds_read_b128 v[172:175], v87 offset:2304
	ds_read_b128 v[176:179], v87 offset:3456
	ds_read_b128 v[180:183], v87 offset:4608
	ds_read_b128 v[184:187], v87 offset:5760
	ds_read_b128 v[188:191], v87 offset:6912
	ds_read_b128 v[192:195], v87 offset:8064
	s_waitcnt lgkmcnt(7)
	global_store_dwordx4 v88, v[164:167], s[50:51] nt
	s_waitcnt lgkmcnt(6)
	global_store_dwordx4 v88, v[168:171], s[50:51] offset:1024 nt
	s_waitcnt lgkmcnt(5)
	global_store_dwordx4 v88, v[172:175], s[50:51] offset:2048 nt
	s_waitcnt lgkmcnt(4)
	global_store_dwordx4 v88, v[176:179], s[50:51] offset:3072 nt
	s_waitcnt lgkmcnt(3)
	global_store_dwordx4 v88, v[180:183], s[8:9] nt
	s_waitcnt lgkmcnt(2)
	global_store_dwordx4 v88, v[184:187], s[8:9] offset:1024 nt
	s_waitcnt lgkmcnt(1)
	global_store_dwordx4 v88, v[188:191], s[8:9] offset:2048 nt
	s_waitcnt lgkmcnt(0)
	global_store_dwordx4 v88, v[192:195], s[8:9] offset:3072 nt
	s_add_i32 s41, s41, -1
	s_cmp_lg_u32 s41, 0
	s_cbranch_scc1 .Lcvh_loop
	s_mov_b64 s[50:51], s[48:49]
	s_add_i32 s2, s2, 8
	s_min_u32 s12, s2, s86
	s_mov_b64 s[10:11], s[80:81]
	s_movk_i32 s4, 0x1000
	s_mov_b32 s5, 8
	s_mov_b32 s6, 0x8400000
	s_cmpk_lt_u32 s12, 0x1000
	s_cselect_b64 s[10:11], s[78:79], s[10:11]
	s_cselect_b32 s4, 0, s4
	s_cselect_b32 s5, 6, s5
	s_cselect_b32 s6, 0x6400000, s6
	s_cmpk_lt_u32 s12, 0x5000
	s_cselect_b64 s[10:11], s[10:11], s[82:83]
	s_cselect_b32 s4, s4, 0x5000
	s_cselect_b32 s5, s5, 6
	s_cselect_b32 s6, s6, 0x10400000
	s_cselect_b32 s7, 6, 8
	s_sub_i32 s12, s12, s4
	s_lshr_b32 s4, s12, s5
	s_bfm_b32 s8, s5, 0
	s_and_b32 s12, s12, s8
	s_lshr_b32 s8, s12, 2
	s_lshl_b32 s8, s8, s7
	s_add_i32 s8, s8, s4
	s_lshl_b32 s8, s8, 15
	s_and_b32 s9, s12, 3
	s_lshl_b32 s9, s9, 13
	s_add_i32 s8, s8, s9
	s_add_u32 s8, s8, s6
	s_add_u32 s48, s8, s16
	s_addc_u32 s49, s17, 0
	s_add_i32 s7, s5, 14
	s_lshl_b32 s4, s4, s7
	s_lshl_b32 s12, s12, 8
	s_add_i32 s4, s4, s12
	s_add_u32 s10, s10, s4
	s_addc_u32 s11, s11, 0
	s_add_i32 s7, s5, 8
	s_lshl_b32 s43, 1, s7
	s_mul_i32 s45, s43, 25
	s_lshl_b32 s47, s43, 3
	v_mad_u32_u24 v89, v84, s47, v85
	global_load_dwordx4 v[100:103], v89, s[10:11] nt
	s_add_u32 s10, s10, s43
	s_addc_u32 s11, s11, 0
	global_load_dwordx4 v[104:107], v89, s[10:11] nt
	s_add_u32 s10, s10, s43
	s_addc_u32 s11, s11, 0
	global_load_dwordx4 v[108:111], v89, s[10:11] nt
	s_add_u32 s10, s10, s43
	s_addc_u32 s11, s11, 0
	global_load_dwordx4 v[112:115], v89, s[10:11] nt
	s_add_u32 s10, s10, s43
	s_addc_u32 s11, s11, 0
	global_load_dwordx4 v[116:119], v89, s[10:11] nt
	s_add_u32 s10, s10, s43
	s_addc_u32 s11, s11, 0
	global_load_dwordx4 v[120:123], v89, s[10:11] nt
	s_add_u32 s10, s10, s43
	s_addc_u32 s11, s11, 0
	global_load_dwordx4 v[124:127], v89, s[10:11] nt
	s_add_u32 s10, s10, s43
	s_addc_u32 s11, s11, 0
	global_load_dwordx4 v[128:131], v89, s[10:11] nt
	s_add_u32 s10, s10, s45
	s_addc_u32 s11, s11, 0
	global_load_dwordx4 v[132:135], v89, s[10:11] nt
	s_add_u32 s10, s10, s43
	s_addc_u32 s11, s11, 0
	global_load_dwordx4 v[136:139], v89, s[10:11] nt
	s_add_u32 s10, s10, s43
	s_addc_u32 s11, s11, 0
	global_load_dwordx4 v[140:143], v89, s[10:11] nt
	s_add_u32 s10, s10, s43
	s_addc_u32 s11, s11, 0
	global_load_dwordx4 v[144:147], v89, s[10:11] nt
	s_add_u32 s10, s10, s43
	s_addc_u32 s11, s11, 0
	global_load_dwordx4 v[148:151], v89, s[10:11] nt
	s_add_u32 s10, s10, s43
	s_addc_u32 s11, s11, 0
	global_load_dwordx4 v[152:155], v89, s[10:11] nt
	s_add_u32 s10, s10, s43
	s_addc_u32 s11, s11, 0
	global_load_dwordx4 v[156:159], v89, s[10:11] nt
	s_add_u32 s10, s10, s43
	s_addc_u32 s11, s11, 0
	global_load_dwordx4 v[160:163], v89, s[10:11] nt
	s_waitcnt vmcnt(16)
	v_cvt_pk_bf16_f32 v164, v20, v24
	v_cvt_pk_bf16_f32 v165, v28, v32
	v_cvt_pk_bf16_f32 v166, v36, v40
	v_cvt_pk_bf16_f32 v167, v44, v48
	ds_write_b128 v86, v[164:167]
	v_cvt_pk_bf16_f32 v168, v21, v25
	v_cvt_pk_bf16_f32 v169, v29, v33
	v_cvt_pk_bf16_f32 v170, v37, v41
	v_cvt_pk_bf16_f32 v171, v45, v49
	ds_write_b128 v86, v[168:171] offset:144
	v_cvt_pk_bf16_f32 v172, v22, v26
	v_cvt_pk_bf16_f32 v173, v30, v34
	v_cvt_pk_bf16_f32 v174, v38, v42
	v_cvt_pk_bf16_f32 v175, v46, v50
	ds_write_b128 v86, v[172:175] offset:288
	v_cvt_pk_bf16_f32 v176, v23, v27
	v_cvt_pk_bf16_f32 v177, v31, v35
	v_cvt_pk_bf16_f32 v178, v39, v43
	v_cvt_pk_bf16_f32 v179, v47, v51
	ds_write_b128 v86, v[176:179] offset:432
	v_cvt_pk_bf16_f32 v180, v52, v56
	v_cvt_pk_bf16_f32 v181, v60, v64
	v_cvt_pk_bf16_f32 v182, v68, v72
	v_cvt_pk_bf16_f32 v183, v76, v80
	ds_write_b128 v86, v[180:183] offset:64
	v_cvt_pk_bf16_f32 v184, v53, v57
	v_cvt_pk_bf16_f32 v185, v61, v65
	v_cvt_pk_bf16_f32 v186, v69, v73
	v_cvt_pk_bf16_f32 v187, v77, v81
	ds_write_b128 v86, v[184:187] offset:208
	v_cvt_pk_bf16_f32 v188, v54, v58
	v_cvt_pk_bf16_f32 v189, v62, v66
	v_cvt_pk_bf16_f32 v190, v70, v74
	v_cvt_pk_bf16_f32 v191, v78, v82
	ds_write_b128 v86, v[188:191] offset:352
	v_cvt_pk_bf16_f32 v192, v55, v59
	v_cvt_pk_bf16_f32 v193, v63, v67
	v_cvt_pk_bf16_f32 v194, v71, v75
	v_cvt_pk_bf16_f32 v195, v79, v83
	ds_write_b128 v86, v[192:195] offset:496
	s_add_u32 s8, s50, 0x1000
	s_addc_u32 s9, s51, 0
	s_waitcnt lgkmcnt(0)
	ds_read_b128 v[164:167], v87
	ds_read_b128 v[168:171], v87 offset:1152
	ds_read_b128 v[172:175], v87 offset:2304
	ds_read_b128 v[176:179], v87 offset:3456
	ds_read_b128 v[180:183], v87 offset:4608
	ds_read_b128 v[184:187], v87 offset:5760
	ds_read_b128 v[188:191], v87 offset:6912
	ds_read_b128 v[192:195], v87 offset:8064
	s_waitcnt lgkmcnt(7)
	global_store_dwordx4 v88, v[164:167], s[50:51] nt
	s_waitcnt lgkmcnt(6)
	global_store_dwordx4 v88, v[168:171], s[50:51] offset:1024 nt
	s_waitcnt lgkmcnt(5)
	global_store_dwordx4 v88, v[172:175], s[50:51] offset:2048 nt
	s_waitcnt lgkmcnt(4)
	global_store_dwordx4 v88, v[176:179], s[50:51] offset:3072 nt
	s_waitcnt lgkmcnt(3)
	global_store_dwordx4 v88, v[180:183], s[8:9] nt
	s_waitcnt lgkmcnt(2)
	global_store_dwordx4 v88, v[184:187], s[8:9] offset:1024 nt
	s_waitcnt lgkmcnt(1)
	global_store_dwordx4 v88, v[188:191], s[8:9] offset:2048 nt
	s_waitcnt lgkmcnt(0)
	global_store_dwordx4 v88, v[192:195], s[8:9] offset:3072 nt
	s_mov_b64 s[50:51], s[48:49]
	s_waitcnt vmcnt(8)
	v_cvt_pk_bf16_f32 v164, v100, v104
	v_cvt_pk_bf16_f32 v165, v108, v112
	v_cvt_pk_bf16_f32 v166, v116, v120
	v_cvt_pk_bf16_f32 v167, v124, v128
	ds_write_b128 v86, v[164:167]
	v_cvt_pk_bf16_f32 v168, v101, v105
	v_cvt_pk_bf16_f32 v169, v109, v113
	v_cvt_pk_bf16_f32 v170, v117, v121
	v_cvt_pk_bf16_f32 v171, v125, v129
	ds_write_b128 v86, v[168:171] offset:144
	v_cvt_pk_bf16_f32 v172, v102, v106
	v_cvt_pk_bf16_f32 v173, v110, v114
	v_cvt_pk_bf16_f32 v174, v118, v122
	v_cvt_pk_bf16_f32 v175, v126, v130
	ds_write_b128 v86, v[172:175] offset:288
	v_cvt_pk_bf16_f32 v176, v103, v107
	v_cvt_pk_bf16_f32 v177, v111, v115
	v_cvt_pk_bf16_f32 v178, v119, v123
	v_cvt_pk_bf16_f32 v179, v127, v131
	ds_write_b128 v86, v[176:179] offset:432
	v_cvt_pk_bf16_f32 v180, v132, v136
	v_cvt_pk_bf16_f32 v181, v140, v144
	v_cvt_pk_bf16_f32 v182, v148, v152
	v_cvt_pk_bf16_f32 v183, v156, v160
	ds_write_b128 v86, v[180:183] offset:64
	v_cvt_pk_bf16_f32 v184, v133, v137
	v_cvt_pk_bf16_f32 v185, v141, v145
	v_cvt_pk_bf16_f32 v186, v149, v153
	v_cvt_pk_bf16_f32 v187, v157, v161
	ds_write_b128 v86, v[184:187] offset:208
	v_cvt_pk_bf16_f32 v188, v134, v138
	v_cvt_pk_bf16_f32 v189, v142, v146
	v_cvt_pk_bf16_f32 v190, v150, v154
	v_cvt_pk_bf16_f32 v191, v158, v162
	ds_write_b128 v86, v[188:191] offset:352
	v_cvt_pk_bf16_f32 v192, v135, v139
	v_cvt_pk_bf16_f32 v193, v143, v147
	v_cvt_pk_bf16_f32 v194, v151, v155
	v_cvt_pk_bf16_f32 v195, v159, v163
	ds_write_b128 v86, v[192:195] offset:496
	s_add_u32 s8, s50, 0x1000
	s_addc_u32 s9, s51, 0
	s_waitcnt lgkmcnt(0)
	ds_read_b128 v[164:167], v87
	ds_read_b128 v[168:171], v87 offset:1152
	ds_read_b128 v[172:175], v87 offset:2304
	ds_read_b128 v[176:179], v87 offset:3456
	ds_read_b128 v[180:183], v87 offset:4608
	ds_read_b128 v[184:187], v87 offset:5760
	ds_read_b128 v[188:191], v87 offset:6912
	ds_read_b128 v[192:195], v87 offset:8064
	s_waitcnt lgkmcnt(7)
	global_store_dwordx4 v88, v[164:167], s[50:51] nt
	s_waitcnt lgkmcnt(6)
	global_store_dwordx4 v88, v[168:171], s[50:51] offset:1024 nt
	s_waitcnt lgkmcnt(5)
	global_store_dwordx4 v88, v[172:175], s[50:51] offset:2048 nt
	s_waitcnt lgkmcnt(4)
	global_store_dwordx4 v88, v[176:179], s[50:51] offset:3072 nt
	s_waitcnt lgkmcnt(3)
	global_store_dwordx4 v88, v[180:183], s[8:9] nt
	s_waitcnt lgkmcnt(2)
	global_store_dwordx4 v88, v[184:187], s[8:9] offset:1024 nt
	s_waitcnt lgkmcnt(1)
	global_store_dwordx4 v88, v[188:191], s[8:9] offset:2048 nt
	s_waitcnt lgkmcnt(0)
	global_store_dwordx4 v88, v[192:195], s[8:9] offset:3072 nt
	s_branch .LBB0_280
